# WKV scan step: value pair read with one ds_read2_b32 and y pair written with one ds_write2_b32 (2 fewer LDS instructions per step)
# speedup vs baseline: 1.0121x; 1.0017x over previous
; __device__ __forceinline__ float red4(float x) { x += dppf(x, 0); x += dppf(x, 1); return x; }
; __device__ __forceinline__ void scan_phase(const Params& p, int j, unsigned char* smem) {
;     ...
;             for (int t = 0; t < 16; ++t) {
;                 const float* op = OPS + t * 320 + kq * 16;
;                 f32x4 A4[4], B4[4], W4[4], K4[4], R4[4];
; #pragma unroll
;                 for (int i = 0; i < 4; ++i) A4[i] = *(const f32x4*)(op + i * 4);
; #pragma unroll
;                 for (int i = 0; i < 4; ++i) { W4[i] = *(const f32x4*)(op + 128 + i * 4); B4[i] = *(const f32x4*)(op + 64 + i * 4); K4[i] = *(const f32x4*)(op + 192 + i * 4); }
; #pragma unroll
;                 for (int i = 0; i < 4; ++i) R4[i] = *(const f32x4*)(op + 256 + i * 4);
;                 const float vv = VB[t * 64 + vrow];
;                 f32x2 s0 = {0.f, 0.f}, s1 = {0.f, 0.f};
; #pragma unroll
;                 for (int i = 0; i < 4; ++i) { s0 += S[2 * i] * (f32x2){A4[i][0], A4[i][1]}; s1 += S[2 * i + 1] * (f32x2){A4[i][2], A4[i][3]}; }
;                 const float sa = red4((s0[0] + s0[1]) + (s1[0] + s1[1]));
;                 const f32x2 sa2 = {sa, sa}, vv2 = {vv, vv};
; #pragma unroll
;                 for (int i = 0; i < 4; ++i) {
;                     S[2 * i] = S[2 * i] * (f32x2){W4[i][0], W4[i][1]} + sa2 * (f32x2){B4[i][0], B4[i][1]} + vv2 * (f32x2){K4[i][0], K4[i][1]};
;                     S[2 * i + 1] = S[2 * i + 1] * (f32x2){W4[i][2], W4[i][3]} + sa2 * (f32x2){B4[i][2], B4[i][3]} + vv2 * (f32x2){K4[i][2], K4[i][3]};
.LBB0_509:
	v_lshlrev_b32_e32 v66, 2, v226
	v_and_b32_e32 v66, 32, v66
	v_add3_u32 v64, v23, v59, v66
	v_and_b32_e32 v66, 8, v226
	v_sub_u32_e32 v65, v62, v66
	v_lshl_add_u32 v65, s10, 2, v65
	s_movk_i32 s7, 0xf000
	s_waitcnt lgkmcnt(0)
	s_barrier
	v_add_u32_e32 v66, s7, v65
	v_add_u32_e32 v67, 0x6200, v66
	v_add_u32_e32 v172, 0x8000, v66
	ds_read_b128 v[68:71], v64
	ds_read_b128 v[72:75], v64 offset:16
	ds_read_b128 v[76:79], v64 offset:256
	ds_read_b128 v[80:83], v64 offset:272
	ds_read_b128 v[84:87], v64 offset:512
	ds_read_b128 v[88:91], v64 offset:528
	ds_read_b128 v[92:95], v64 offset:768
	ds_read_b128 v[96:99], v64 offset:784
	ds_read_b128 v[100:103], v64 offset:1024
	ds_read_b128 v[104:107], v64 offset:1040
	ds_read_b32 v108, v66 offset:24576
	ds_read_b32 v109, v66 offset:24584
	s_waitcnt lgkmcnt(0)
	ds_read_b128 v[112:115], v64 offset:1280
	ds_read_b128 v[116:119], v64 offset:1296
	ds_read_b128 v[120:123], v64 offset:1536
	ds_read_b128 v[124:127], v64 offset:1552
	ds_read_b128 v[128:131], v64 offset:1792
	ds_read_b128 v[132:135], v64 offset:1808
	ds_read_b128 v[136:139], v64 offset:2048
	ds_read_b128 v[140:143], v64 offset:2064
	ds_read_b128 v[144:147], v64 offset:2304
	ds_read_b128 v[148:151], v64 offset:2320
	ds_read_b32 v152, v66 offset:24832
	ds_read_b32 v153, v66 offset:24840
	s_branch .LBB0_511
.LBB0_510:
	s_addk_i32 s7, 0x400
	s_cmp_eq_u32 s7, 0
	v_add_u32_e32 v64, 0x1400, v64
	s_cbranch_scc1 .LBB0_504
	v_add_u32_e32 v66, s7, v65
	v_add_u32_e32 v67, 0x6200, v66
	v_add_u32_e32 v172, 0x8000, v66
.LBB0_511:
	v_pk_mul_f32 v[156:157], v[38:39], v[68:69]
	v_pk_mul_f32 v[158:159], v[46:47], v[68:69]
	v_pk_fma_f32 v[156:157], v[40:41], v[70:71], v[156:157]
	v_pk_fma_f32 v[158:159], v[48:49], v[70:71], v[158:159]
	v_pk_fma_f32 v[156:157], v[42:43], v[72:73], v[156:157]
	v_pk_fma_f32 v[158:159], v[50:51], v[72:73], v[158:159]
	v_pk_fma_f32 v[156:157], v[44:45], v[74:75], v[156:157]
	v_pk_fma_f32 v[158:159], v[52:53], v[74:75], v[158:159]
	v_add_f32_e32 v156, v156, v157
	v_add_f32_e32 v158, v158, v159
	v_pk_mul_f32 v[38:39], v[38:39], v[84:85]
	v_add_f32_dpp v168, v156, v156 quad_perm:[1,0,3,2] row_mask:0xf bank_mask:0xf bound_ctrl:1
	v_add_f32_dpp v169, v158, v158 quad_perm:[1,0,3,2] row_mask:0xf bank_mask:0xf bound_ctrl:1
	v_pk_mul_f32 v[46:47], v[46:47], v[84:85]
	v_add_f32_dpp v170, v168, v168 quad_perm:[2,3,0,1] row_mask:0xf bank_mask:0xf bound_ctrl:1
	v_add_f32_dpp v171, v169, v169 quad_perm:[2,3,0,1] row_mask:0xf bank_mask:0xf bound_ctrl:1
	v_pk_mul_f32 v[40:41], v[40:41], v[86:87]
	v_add_f32_dpp v160, v170, v170 row_ror:8 row_mask:0xf bank_mask:0xf
	v_add_f32_dpp v162, v171, v171 row_ror:8 row_mask:0xf bank_mask:0xf
	v_pk_mul_f32 v[48:49], v[48:49], v[86:87]
	v_pk_mul_f32 v[42:43], v[42:43], v[88:89]
	v_pk_mul_f32 v[50:51], v[50:51], v[88:89]
	v_pk_mul_f32 v[44:45], v[44:45], v[90:91]
	v_pk_mul_f32 v[52:53], v[52:53], v[90:91]
	v_pk_fma_f32 v[38:39], v[76:77], v[160:161], v[38:39] op_sel_hi:[1,0,1]
	v_pk_fma_f32 v[46:47], v[76:77], v[162:163], v[46:47] op_sel_hi:[1,0,1]
	v_pk_fma_f32 v[40:41], v[78:79], v[160:161], v[40:41] op_sel_hi:[1,0,1]
	v_pk_fma_f32 v[48:49], v[78:79], v[162:163], v[48:49] op_sel_hi:[1,0,1]
	v_pk_fma_f32 v[42:43], v[80:81], v[160:161], v[42:43] op_sel_hi:[1,0,1]
	v_pk_fma_f32 v[50:51], v[80:81], v[162:163], v[50:51] op_sel_hi:[1,0,1]
	v_pk_fma_f32 v[44:45], v[82:83], v[160:161], v[44:45] op_sel_hi:[1,0,1]
	v_pk_fma_f32 v[52:53], v[82:83], v[162:163], v[52:53] op_sel_hi:[1,0,1]
	v_pk_fma_f32 v[38:39], v[92:93], v[108:109], v[38:39] op_sel_hi:[1,0,1]
	v_pk_fma_f32 v[46:47], v[92:93], v[108:109], v[46:47] op_sel:[0,1,0] op_sel_hi:[1,1,1]
	v_pk_fma_f32 v[40:41], v[94:95], v[108:109], v[40:41] op_sel_hi:[1,0,1]
	v_pk_fma_f32 v[48:49], v[94:95], v[108:109], v[48:49] op_sel:[0,1,0] op_sel_hi:[1,1,1]
	v_pk_fma_f32 v[42:43], v[96:97], v[108:109], v[42:43] op_sel_hi:[1,0,1]
	v_pk_fma_f32 v[50:51], v[96:97], v[108:109], v[50:51] op_sel:[0,1,0] op_sel_hi:[1,1,1]
	v_pk_fma_f32 v[44:45], v[98:99], v[108:109], v[44:45] op_sel_hi:[1,0,1]
	v_pk_fma_f32 v[52:53], v[98:99], v[108:109], v[52:53] op_sel:[0,1,0] op_sel_hi:[1,1,1]
	v_pk_mul_f32 v[164:165], v[38:39], v[100:101]
	v_pk_mul_f32 v[166:167], v[46:47], v[100:101]
	v_pk_fma_f32 v[164:165], v[40:41], v[102:103], v[164:165]
	v_pk_fma_f32 v[166:167], v[48:49], v[102:103], v[166:167]
	v_pk_fma_f32 v[164:165], v[42:43], v[104:105], v[164:165]
	v_pk_fma_f32 v[166:167], v[50:51], v[104:105], v[166:167]
	v_pk_fma_f32 v[164:165], v[44:45], v[106:107], v[164:165]
	v_pk_fma_f32 v[166:167], v[52:53], v[106:107], v[166:167]
	v_add_f32_e32 v164, v164, v165
	v_add_f32_e32 v166, v166, v167
	s_waitcnt lgkmcnt(0)
; __device__ __forceinline__ float red4(float x) { x += dppf(x, 0); x += dppf(x, 1); return x; }
; __device__ __forceinline__ void scan_phase(const Params& p, int j, unsigned char* smem) {
;     ...
;             for (int t = 0; t < 16; ++t) {
;                 const float* op = OPS + t * 320 + kq * 16;
;                 f32x4 A4[4], B4[4], W4[4], K4[4], R4[4];
; #pragma unroll
;                 for (int i = 0; i < 4; ++i) A4[i] = *(const f32x4*)(op + i * 4);
; #pragma unroll
;                 for (int i = 0; i < 4; ++i) { W4[i] = *(const f32x4*)(op + 128 + i * 4); B4[i] = *(const f32x4*)(op + 64 + i * 4); K4[i] = *(const f32x4*)(op + 192 + i * 4); }
; #pragma unroll
;                 for (int i = 0; i < 4; ++i) R4[i] = *(const f32x4*)(op + 256 + i * 4);
;                 const float vv = VB[t * 64 + vrow];
;                 f32x2 s0 = {0.f, 0.f}, s1 = {0.f, 0.f};
; #pragma unroll
;                 for (int i = 0; i < 4; ++i) { s0 += S[2 * i] * (f32x2){A4[i][0], A4[i][1]}; s1 += S[2 * i + 1] * (f32x2){A4[i][2], A4[i][3]}; }
;                 const float sa = red4((s0[0] + s0[1]) + (s1[0] + s1[1]));
;                 const f32x2 sa2 = {sa, sa}, vv2 = {vv, vv};
; #pragma unroll
;                 for (int i = 0; i < 4; ++i) {
;                     S[2 * i] = S[2 * i] * (f32x2){W4[i][0], W4[i][1]} + sa2 * (f32x2){B4[i][0], B4[i][1]} + vv2 * (f32x2){K4[i][0], K4[i][1]};
;                     S[2 * i + 1] = S[2 * i + 1] * (f32x2){W4[i][2], W4[i][3]} + sa2 * (f32x2){B4[i][2], B4[i][3]} + vv2 * (f32x2){K4[i][2], K4[i][3]};
;                 }
;                 f32x2 y0 = {0.f, 0.f}, y1 = {0.f, 0.f};
; #pragma unroll
;                 for (int i = 0; i < 4; ++i) { y0 += S[2 * i] * (f32x2){R4[i][0], R4[i][1]}; y1 += S[2 * i + 1] * (f32x2){R4[i][2], R4[i][3]}; }
;                 const float y = red4((y0[0] + y0[1]) + (y1[0] + y1[1]));
;                 if (kq == 0) YB[t * 64 + vrow] = y;
	ds_read_b128 v[68:71], v64 offset:2560
	v_add_f32_dpp v168, v164, v164 quad_perm:[1,0,3,2] row_mask:0xf bank_mask:0xf bound_ctrl:1
	v_add_f32_dpp v169, v166, v166 quad_perm:[1,0,3,2] row_mask:0xf bank_mask:0xf bound_ctrl:1
	ds_read_b128 v[72:75], v64 offset:2576
	v_add_f32_dpp v170, v168, v168 quad_perm:[2,3,0,1] row_mask:0xf bank_mask:0xf bound_ctrl:1
	v_add_f32_dpp v171, v169, v169 quad_perm:[2,3,0,1] row_mask:0xf bank_mask:0xf bound_ctrl:1
	ds_read_b128 v[76:79], v64 offset:2816
	v_add_f32_dpp v164, v170, v170 row_ror:8 row_mask:0xf bank_mask:0xf
	v_add_f32_dpp v166, v171, v171 row_ror:8 row_mask:0xf bank_mask:0xf
	ds_read_b128 v[80:83], v64 offset:2832
	ds_read_b128 v[84:87], v64 offset:3072
	ds_read_b128 v[88:91], v64 offset:3088
	ds_read_b128 v[92:95], v64 offset:3328
	ds_read_b128 v[96:99], v64 offset:3344
	ds_read_b128 v[100:103], v64 offset:3584
	ds_read_b128 v[104:107], v64 offset:3600
	ds_read2_b32 v[108:109], v67 offset0:0 offset1:2
	ds_write2_b32 v172, v164, v166 offset0:0 offset1:2
	v_pk_mul_f32 v[156:157], v[38:39], v[112:113]
	v_pk_mul_f32 v[158:159], v[46:47], v[112:113]
	v_pk_fma_f32 v[156:157], v[40:41], v[114:115], v[156:157]
	v_pk_fma_f32 v[158:159], v[48:49], v[114:115], v[158:159]
	v_pk_fma_f32 v[156:157], v[42:43], v[116:117], v[156:157]
	v_pk_fma_f32 v[158:159], v[50:51], v[116:117], v[158:159]
	v_pk_fma_f32 v[156:157], v[44:45], v[118:119], v[156:157]
	v_pk_fma_f32 v[158:159], v[52:53], v[118:119], v[158:159]
	v_add_f32_e32 v156, v156, v157
	v_add_f32_e32 v158, v158, v159
	v_pk_mul_f32 v[38:39], v[38:39], v[128:129]
	v_add_f32_dpp v168, v156, v156 quad_perm:[1,0,3,2] row_mask:0xf bank_mask:0xf bound_ctrl:1
	v_add_f32_dpp v169, v158, v158 quad_perm:[1,0,3,2] row_mask:0xf bank_mask:0xf bound_ctrl:1
	v_pk_mul_f32 v[46:47], v[46:47], v[128:129]
	v_add_f32_dpp v170, v168, v168 quad_perm:[2,3,0,1] row_mask:0xf bank_mask:0xf bound_ctrl:1
	v_add_f32_dpp v171, v169, v169 quad_perm:[2,3,0,1] row_mask:0xf bank_mask:0xf bound_ctrl:1
	v_pk_mul_f32 v[40:41], v[40:41], v[130:131]
	v_add_f32_dpp v160, v170, v170 row_ror:8 row_mask:0xf bank_mask:0xf
	v_add_f32_dpp v162, v171, v171 row_ror:8 row_mask:0xf bank_mask:0xf
	v_pk_mul_f32 v[48:49], v[48:49], v[130:131]
	v_pk_mul_f32 v[42:43], v[42:43], v[132:133]
	v_pk_mul_f32 v[50:51], v[50:51], v[132:133]
	v_pk_mul_f32 v[44:45], v[44:45], v[134:135]
	v_pk_mul_f32 v[52:53], v[52:53], v[134:135]
	v_pk_fma_f32 v[38:39], v[120:121], v[160:161], v[38:39] op_sel_hi:[1,0,1]
	v_pk_fma_f32 v[46:47], v[120:121], v[162:163], v[46:47] op_sel_hi:[1,0,1]
	v_pk_fma_f32 v[40:41], v[122:123], v[160:161], v[40:41] op_sel_hi:[1,0,1]
	v_pk_fma_f32 v[48:49], v[122:123], v[162:163], v[48:49] op_sel_hi:[1,0,1]
	v_pk_fma_f32 v[42:43], v[124:125], v[160:161], v[42:43] op_sel_hi:[1,0,1]
	v_pk_fma_f32 v[50:51], v[124:125], v[162:163], v[50:51] op_sel_hi:[1,0,1]
	v_pk_fma_f32 v[44:45], v[126:127], v[160:161], v[44:45] op_sel_hi:[1,0,1]
	v_pk_fma_f32 v[52:53], v[126:127], v[162:163], v[52:53] op_sel_hi:[1,0,1]
	v_pk_fma_f32 v[38:39], v[136:137], v[152:153], v[38:39] op_sel_hi:[1,0,1]
	v_pk_fma_f32 v[46:47], v[136:137], v[152:153], v[46:47] op_sel:[0,1,0] op_sel_hi:[1,1,1]
	v_pk_fma_f32 v[40:41], v[138:139], v[152:153], v[40:41] op_sel_hi:[1,0,1]
	v_pk_fma_f32 v[48:49], v[138:139], v[152:153], v[48:49] op_sel:[0,1,0] op_sel_hi:[1,1,1]
	v_pk_fma_f32 v[42:43], v[140:141], v[152:153], v[42:43] op_sel_hi:[1,0,1]
	v_pk_fma_f32 v[50:51], v[140:141], v[152:153], v[50:51] op_sel:[0,1,0] op_sel_hi:[1,1,1]
	v_pk_fma_f32 v[44:45], v[142:143], v[152:153], v[44:45] op_sel_hi:[1,0,1]
	v_pk_fma_f32 v[52:53], v[142:143], v[152:153], v[52:53] op_sel:[0,1,0] op_sel_hi:[1,1,1]
	v_pk_mul_f32 v[164:165], v[38:39], v[144:145]
	v_pk_mul_f32 v[166:167], v[46:47], v[144:145]
	v_pk_fma_f32 v[164:165], v[40:41], v[146:147], v[164:165]
	v_pk_fma_f32 v[166:167], v[48:49], v[146:147], v[166:167]
	v_pk_fma_f32 v[164:165], v[42:43], v[148:149], v[164:165]
	v_pk_fma_f32 v[166:167], v[50:51], v[148:149], v[166:167]
	v_pk_fma_f32 v[164:165], v[44:45], v[150:151], v[164:165]
	v_pk_fma_f32 v[166:167], v[52:53], v[150:151], v[166:167]
	v_add_f32_e32 v164, v164, v165
	v_add_f32_e32 v166, v166, v167
	s_waitcnt lgkmcnt(0)
	ds_read_b128 v[112:115], v64 offset:3840
	v_add_f32_dpp v168, v164, v164 quad_perm:[1,0,3,2] row_mask:0xf bank_mask:0xf bound_ctrl:1
	v_add_f32_dpp v169, v166, v166 quad_perm:[1,0,3,2] row_mask:0xf bank_mask:0xf bound_ctrl:1
	ds_read_b128 v[116:119], v64 offset:3856
	v_add_f32_dpp v170, v168, v168 quad_perm:[2,3,0,1] row_mask:0xf bank_mask:0xf bound_ctrl:1
	v_add_f32_dpp v171, v169, v169 quad_perm:[2,3,0,1] row_mask:0xf bank_mask:0xf bound_ctrl:1
	ds_read_b128 v[120:123], v64 offset:4096
	v_add_f32_dpp v164, v170, v170 row_ror:8 row_mask:0xf bank_mask:0xf
	v_add_f32_dpp v166, v171, v171 row_ror:8 row_mask:0xf bank_mask:0xf
	ds_read_b128 v[124:127], v64 offset:4112
	ds_read_b128 v[128:131], v64 offset:4352
	ds_read_b128 v[132:135], v64 offset:4368
	ds_read_b128 v[136:139], v64 offset:4608
	ds_read_b128 v[140:143], v64 offset:4624
	ds_read_b128 v[144:147], v64 offset:4864
	ds_read_b128 v[148:151], v64 offset:4880
	ds_read2_b32 v[152:153], v67 offset0:64 offset1:66
	ds_write2_b32 v172, v164, v166 offset0:64 offset1:66
	v_pk_mul_f32 v[156:157], v[38:39], v[68:69]
	v_pk_mul_f32 v[158:159], v[46:47], v[68:69]
	v_pk_fma_f32 v[156:157], v[40:41], v[70:71], v[156:157]
	v_pk_fma_f32 v[158:159], v[48:49], v[70:71], v[158:159]
	v_pk_fma_f32 v[156:157], v[42:43], v[72:73], v[156:157]
	v_pk_fma_f32 v[158:159], v[50:51], v[72:73], v[158:159]
	v_pk_fma_f32 v[156:157], v[44:45], v[74:75], v[156:157]
	v_pk_fma_f32 v[158:159], v[52:53], v[74:75], v[158:159]
; __device__ __forceinline__ float red4(float x) { x += dppf(x, 0); x += dppf(x, 1); return x; }
; __device__ __forceinline__ void scan_phase(const Params& p, int j, unsigned char* smem) {
;     ...
;                 const float vv = VB[t * 64 + vrow];
;                 f32x2 s0 = {0.f, 0.f}, s1 = {0.f, 0.f};
; #pragma unroll
;                 for (int i = 0; i < 4; ++i) { s0 += S[2 * i] * (f32x2){A4[i][0], A4[i][1]}; s1 += S[2 * i + 1] * (f32x2){A4[i][2], A4[i][3]}; }
;                 const float sa = red4((s0[0] + s0[1]) + (s1[0] + s1[1]));
;                 const f32x2 sa2 = {sa, sa}, vv2 = {vv, vv};
; #pragma unroll
;                 for (int i = 0; i < 4; ++i) {
;                     S[2 * i] = S[2 * i] * (f32x2){W4[i][0], W4[i][1]} + sa2 * (f32x2){B4[i][0], B4[i][1]} + vv2 * (f32x2){K4[i][0], K4[i][1]};
;                     S[2 * i + 1] = S[2 * i + 1] * (f32x2){W4[i][2], W4[i][3]} + sa2 * (f32x2){B4[i][2], B4[i][3]} + vv2 * (f32x2){K4[i][2], K4[i][3]};
;                 }
	v_add_f32_e32 v156, v156, v157
	v_add_f32_e32 v158, v158, v159
	v_pk_mul_f32 v[38:39], v[38:39], v[84:85]
	v_add_f32_dpp v168, v156, v156 quad_perm:[1,0,3,2] row_mask:0xf bank_mask:0xf bound_ctrl:1
	v_add_f32_dpp v169, v158, v158 quad_perm:[1,0,3,2] row_mask:0xf bank_mask:0xf bound_ctrl:1
	v_pk_mul_f32 v[46:47], v[46:47], v[84:85]
	v_add_f32_dpp v170, v168, v168 quad_perm:[2,3,0,1] row_mask:0xf bank_mask:0xf bound_ctrl:1
	v_add_f32_dpp v171, v169, v169 quad_perm:[2,3,0,1] row_mask:0xf bank_mask:0xf bound_ctrl:1
	v_pk_mul_f32 v[40:41], v[40:41], v[86:87]
	v_add_f32_dpp v160, v170, v170 row_ror:8 row_mask:0xf bank_mask:0xf
	v_add_f32_dpp v162, v171, v171 row_ror:8 row_mask:0xf bank_mask:0xf
	v_pk_mul_f32 v[48:49], v[48:49], v[86:87]
	v_pk_mul_f32 v[42:43], v[42:43], v[88:89]
	v_pk_mul_f32 v[50:51], v[50:51], v[88:89]
	v_pk_mul_f32 v[44:45], v[44:45], v[90:91]
	v_pk_mul_f32 v[52:53], v[52:53], v[90:91]
	v_pk_fma_f32 v[38:39], v[76:77], v[160:161], v[38:39] op_sel_hi:[1,0,1]
	v_pk_fma_f32 v[46:47], v[76:77], v[162:163], v[46:47] op_sel_hi:[1,0,1]
	v_pk_fma_f32 v[40:41], v[78:79], v[160:161], v[40:41] op_sel_hi:[1,0,1]
	v_pk_fma_f32 v[48:49], v[78:79], v[162:163], v[48:49] op_sel_hi:[1,0,1]
	v_pk_fma_f32 v[42:43], v[80:81], v[160:161], v[42:43] op_sel_hi:[1,0,1]
	v_pk_fma_f32 v[50:51], v[80:81], v[162:163], v[50:51] op_sel_hi:[1,0,1]
	v_pk_fma_f32 v[44:45], v[82:83], v[160:161], v[44:45] op_sel_hi:[1,0,1]
	v_pk_fma_f32 v[52:53], v[82:83], v[162:163], v[52:53] op_sel_hi:[1,0,1]
	v_pk_fma_f32 v[38:39], v[92:93], v[108:109], v[38:39] op_sel_hi:[1,0,1]
	v_pk_fma_f32 v[46:47], v[92:93], v[108:109], v[46:47] op_sel:[0,1,0] op_sel_hi:[1,1,1]
	v_pk_fma_f32 v[40:41], v[94:95], v[108:109], v[40:41] op_sel_hi:[1,0,1]
	v_pk_fma_f32 v[48:49], v[94:95], v[108:109], v[48:49] op_sel:[0,1,0] op_sel_hi:[1,1,1]
	v_pk_fma_f32 v[42:43], v[96:97], v[108:109], v[42:43] op_sel_hi:[1,0,1]
	v_pk_fma_f32 v[50:51], v[96:97], v[108:109], v[50:51] op_sel:[0,1,0] op_sel_hi:[1,1,1]
	v_pk_fma_f32 v[44:45], v[98:99], v[108:109], v[44:45] op_sel_hi:[1,0,1]
	v_pk_fma_f32 v[52:53], v[98:99], v[108:109], v[52:53] op_sel:[0,1,0] op_sel_hi:[1,1,1]
	v_pk_mul_f32 v[164:165], v[38:39], v[100:101]
	v_pk_mul_f32 v[166:167], v[46:47], v[100:101]
	v_pk_fma_f32 v[164:165], v[40:41], v[102:103], v[164:165]
	v_pk_fma_f32 v[166:167], v[48:49], v[102:103], v[166:167]
	v_pk_fma_f32 v[164:165], v[42:43], v[104:105], v[164:165]
	v_pk_fma_f32 v[166:167], v[50:51], v[104:105], v[166:167]
	v_pk_fma_f32 v[164:165], v[44:45], v[106:107], v[164:165]
	v_pk_fma_f32 v[166:167], v[52:53], v[106:107], v[166:167]
	v_add_f32_e32 v164, v164, v165
	v_add_f32_e32 v166, v166, v167
	s_waitcnt lgkmcnt(0)
; __device__ __forceinline__ float red4(float x) { x += dppf(x, 0); x += dppf(x, 1); return x; }
; __device__ __forceinline__ void scan_phase(const Params& p, int j, unsigned char* smem) {
;     ...
;             for (int t = 0; t < 16; ++t) {
;                 const float* op = OPS + t * 320 + kq * 16;
;                 f32x4 A4[4], B4[4], W4[4], K4[4], R4[4];
; #pragma unroll
;                 for (int i = 0; i < 4; ++i) A4[i] = *(const f32x4*)(op + i * 4);
; #pragma unroll
;                 for (int i = 0; i < 4; ++i) { W4[i] = *(const f32x4*)(op + 128 + i * 4); B4[i] = *(const f32x4*)(op + 64 + i * 4); K4[i] = *(const f32x4*)(op + 192 + i * 4); }
; #pragma unroll
;                 for (int i = 0; i < 4; ++i) R4[i] = *(const f32x4*)(op + 256 + i * 4);
;                 const float vv = VB[t * 64 + vrow];
;                 f32x2 s0 = {0.f, 0.f}, s1 = {0.f, 0.f};
; #pragma unroll
;                 for (int i = 0; i < 4; ++i) { s0 += S[2 * i] * (f32x2){A4[i][0], A4[i][1]}; s1 += S[2 * i + 1] * (f32x2){A4[i][2], A4[i][3]}; }
;                 const float sa = red4((s0[0] + s0[1]) + (s1[0] + s1[1]));
;                 const f32x2 sa2 = {sa, sa}, vv2 = {vv, vv};
; #pragma unroll
;                 for (int i = 0; i < 4; ++i) {
;                     S[2 * i] = S[2 * i] * (f32x2){W4[i][0], W4[i][1]} + sa2 * (f32x2){B4[i][0], B4[i][1]} + vv2 * (f32x2){K4[i][0], K4[i][1]};
;                     S[2 * i + 1] = S[2 * i + 1] * (f32x2){W4[i][2], W4[i][3]} + sa2 * (f32x2){B4[i][2], B4[i][3]} + vv2 * (f32x2){K4[i][2], K4[i][3]};
;                 }
;                 f32x2 y0 = {0.f, 0.f}, y1 = {0.f, 0.f};
; #pragma unroll
;                 for (int i = 0; i < 4; ++i) { y0 += S[2 * i] * (f32x2){R4[i][0], R4[i][1]}; y1 += S[2 * i + 1] * (f32x2){R4[i][2], R4[i][3]}; }
;                 const float y = red4((y0[0] + y0[1]) + (y1[0] + y1[1]));
;                 if (kq == 0) YB[t * 64 + vrow] = y;
	ds_read_b128 v[68:71], v64 offset:5120
	v_add_f32_dpp v168, v164, v164 quad_perm:[1,0,3,2] row_mask:0xf bank_mask:0xf bound_ctrl:1
	v_add_f32_dpp v169, v166, v166 quad_perm:[1,0,3,2] row_mask:0xf bank_mask:0xf bound_ctrl:1
	ds_read_b128 v[72:75], v64 offset:5136
	v_add_f32_dpp v170, v168, v168 quad_perm:[2,3,0,1] row_mask:0xf bank_mask:0xf bound_ctrl:1
	v_add_f32_dpp v171, v169, v169 quad_perm:[2,3,0,1] row_mask:0xf bank_mask:0xf bound_ctrl:1
	ds_read_b128 v[76:79], v64 offset:5376
	v_add_f32_dpp v164, v170, v170 row_ror:8 row_mask:0xf bank_mask:0xf
	v_add_f32_dpp v166, v171, v171 row_ror:8 row_mask:0xf bank_mask:0xf
	ds_read_b128 v[80:83], v64 offset:5392
	ds_read_b128 v[84:87], v64 offset:5632
	ds_read_b128 v[88:91], v64 offset:5648
	ds_read_b128 v[92:95], v64 offset:5888
	ds_read_b128 v[96:99], v64 offset:5904
	ds_read_b128 v[100:103], v64 offset:6144
	ds_read_b128 v[104:107], v64 offset:6160
	ds_read2_b32 v[108:109], v67 offset0:128 offset1:130
	ds_write2_b32 v172, v164, v166 offset0:128 offset1:130
	v_pk_mul_f32 v[156:157], v[38:39], v[112:113]
	v_pk_mul_f32 v[158:159], v[46:47], v[112:113]
	v_pk_fma_f32 v[156:157], v[40:41], v[114:115], v[156:157]
	v_pk_fma_f32 v[158:159], v[48:49], v[114:115], v[158:159]
	v_pk_fma_f32 v[156:157], v[42:43], v[116:117], v[156:157]
	v_pk_fma_f32 v[158:159], v[50:51], v[116:117], v[158:159]
	v_pk_fma_f32 v[156:157], v[44:45], v[118:119], v[156:157]
	v_pk_fma_f32 v[158:159], v[52:53], v[118:119], v[158:159]
	v_add_f32_e32 v156, v156, v157
	v_add_f32_e32 v158, v158, v159
	v_pk_mul_f32 v[38:39], v[38:39], v[128:129]
	v_add_f32_dpp v168, v156, v156 quad_perm:[1,0,3,2] row_mask:0xf bank_mask:0xf bound_ctrl:1
	v_add_f32_dpp v169, v158, v158 quad_perm:[1,0,3,2] row_mask:0xf bank_mask:0xf bound_ctrl:1
	v_pk_mul_f32 v[46:47], v[46:47], v[128:129]
	v_add_f32_dpp v170, v168, v168 quad_perm:[2,3,0,1] row_mask:0xf bank_mask:0xf bound_ctrl:1
	v_add_f32_dpp v171, v169, v169 quad_perm:[2,3,0,1] row_mask:0xf bank_mask:0xf bound_ctrl:1
	v_pk_mul_f32 v[40:41], v[40:41], v[130:131]
	v_add_f32_dpp v160, v170, v170 row_ror:8 row_mask:0xf bank_mask:0xf
	v_add_f32_dpp v162, v171, v171 row_ror:8 row_mask:0xf bank_mask:0xf
	v_pk_mul_f32 v[48:49], v[48:49], v[130:131]
	v_pk_mul_f32 v[42:43], v[42:43], v[132:133]
	v_pk_mul_f32 v[50:51], v[50:51], v[132:133]
	v_pk_mul_f32 v[44:45], v[44:45], v[134:135]
	v_pk_mul_f32 v[52:53], v[52:53], v[134:135]
	v_pk_fma_f32 v[38:39], v[120:121], v[160:161], v[38:39] op_sel_hi:[1,0,1]
	v_pk_fma_f32 v[46:47], v[120:121], v[162:163], v[46:47] op_sel_hi:[1,0,1]
	v_pk_fma_f32 v[40:41], v[122:123], v[160:161], v[40:41] op_sel_hi:[1,0,1]
	v_pk_fma_f32 v[48:49], v[122:123], v[162:163], v[48:49] op_sel_hi:[1,0,1]
	v_pk_fma_f32 v[42:43], v[124:125], v[160:161], v[42:43] op_sel_hi:[1,0,1]
	v_pk_fma_f32 v[50:51], v[124:125], v[162:163], v[50:51] op_sel_hi:[1,0,1]
	v_pk_fma_f32 v[44:45], v[126:127], v[160:161], v[44:45] op_sel_hi:[1,0,1]
	v_pk_fma_f32 v[52:53], v[126:127], v[162:163], v[52:53] op_sel_hi:[1,0,1]
	v_pk_fma_f32 v[38:39], v[136:137], v[152:153], v[38:39] op_sel_hi:[1,0,1]
	v_pk_fma_f32 v[46:47], v[136:137], v[152:153], v[46:47] op_sel:[0,1,0] op_sel_hi:[1,1,1]
	v_pk_fma_f32 v[40:41], v[138:139], v[152:153], v[40:41] op_sel_hi:[1,0,1]
	v_pk_fma_f32 v[48:49], v[138:139], v[152:153], v[48:49] op_sel:[0,1,0] op_sel_hi:[1,1,1]
	v_pk_fma_f32 v[42:43], v[140:141], v[152:153], v[42:43] op_sel_hi:[1,0,1]
	v_pk_fma_f32 v[50:51], v[140:141], v[152:153], v[50:51] op_sel:[0,1,0] op_sel_hi:[1,1,1]
	v_pk_fma_f32 v[44:45], v[142:143], v[152:153], v[44:45] op_sel_hi:[1,0,1]
	v_pk_fma_f32 v[52:53], v[142:143], v[152:153], v[52:53] op_sel:[0,1,0] op_sel_hi:[1,1,1]
	v_pk_mul_f32 v[164:165], v[38:39], v[144:145]
	v_pk_mul_f32 v[166:167], v[46:47], v[144:145]
	v_pk_fma_f32 v[164:165], v[40:41], v[146:147], v[164:165]
	v_pk_fma_f32 v[166:167], v[48:49], v[146:147], v[166:167]
	v_pk_fma_f32 v[164:165], v[42:43], v[148:149], v[164:165]
	v_pk_fma_f32 v[166:167], v[50:51], v[148:149], v[166:167]
	v_pk_fma_f32 v[164:165], v[44:45], v[150:151], v[164:165]
	v_pk_fma_f32 v[166:167], v[52:53], v[150:151], v[166:167]
	v_add_f32_e32 v164, v164, v165
	v_add_f32_e32 v166, v166, v167
	s_waitcnt lgkmcnt(0)
	ds_read_b128 v[112:115], v64 offset:6400
	v_add_f32_dpp v168, v164, v164 quad_perm:[1,0,3,2] row_mask:0xf bank_mask:0xf bound_ctrl:1
	v_add_f32_dpp v169, v166, v166 quad_perm:[1,0,3,2] row_mask:0xf bank_mask:0xf bound_ctrl:1
	ds_read_b128 v[116:119], v64 offset:6416
	v_add_f32_dpp v170, v168, v168 quad_perm:[2,3,0,1] row_mask:0xf bank_mask:0xf bound_ctrl:1
	v_add_f32_dpp v171, v169, v169 quad_perm:[2,3,0,1] row_mask:0xf bank_mask:0xf bound_ctrl:1
	ds_read_b128 v[120:123], v64 offset:6656
	v_add_f32_dpp v164, v170, v170 row_ror:8 row_mask:0xf bank_mask:0xf
	v_add_f32_dpp v166, v171, v171 row_ror:8 row_mask:0xf bank_mask:0xf
	ds_read_b128 v[124:127], v64 offset:6672
	ds_read_b128 v[128:131], v64 offset:6912
	ds_read_b128 v[132:135], v64 offset:6928
	ds_read_b128 v[136:139], v64 offset:7168
	ds_read_b128 v[140:143], v64 offset:7184
	ds_read_b128 v[144:147], v64 offset:7424
	ds_read_b128 v[148:151], v64 offset:7440
	ds_read2_b32 v[152:153], v67 offset0:192 offset1:194
	ds_write2_b32 v172, v164, v166 offset0:192 offset1:194
	s_branch .LBB0_510
